# XCD-local barrier (no L2 writeback / cross-XCD arrival) at the 12 GEMM->GEMM seams whose M-tile ownership keeps producer and consumer on one XCD
# speedup vs baseline: 1.0374x; 1.0213x over previous
.LBB0_290:
	s_andn2_saveexec_b64 s[0:1], s[8:9]
	s_cbranch_execz .LBB0_310
	s_mov_b64 s[8:9], exec
	s_waitcnt lgkmcnt(0)
	s_mov_b64 s[8:9], exec
	v_mbcnt_lo_u32_b32 v0, s8, 0
	v_mbcnt_hi_u32_b32 v0, s9, v0
	v_cmp_eq_u32_e32 vcc, 0, v0
	s_waitcnt vmcnt(0)
	buffer_inv sc1
	s_and_saveexec_b64 s[10:11], vcc
	s_cbranch_execz .LBB0_309
	s_bcnt1_i32_b64 s0, s[8:9]
	v_mov_b32_e32 v0, 0x2000
	v_mov_b32_e32 v1, s0
	global_atomic_add v0, v1, s[6:7] offset:1024
